# P6 GEMM epilogue hand-rewritten too (32 in-place residual loads up front, counted vmcnt, ssq atomics unchanged)
# speedup vs baseline: 1.0361x; 1.0028x over previous
.LBB0_979:
	v_lshl_or_b32 v140, s34, 8, v147
	v_lshl_add_u32 v142, s30, 8, v145
	v_readlane_b32 s56, v237, 0
	v_readlane_b32 s57, v237, 1
	v_readlane_b32 s58, v237, 2
	v_readlane_b32 s59, v237, 3
	v_readlane_b32 s60, v237, 4
	v_readlane_b32 s61, v237, 5
	v_readlane_b32 s62, v237, 6
	v_readlane_b32 s63, v237, 7
	v_lshlrev_b32_e32 v143, 1, v140
	v_lshl_add_u32 v143, v142, 12, v143
	v_xor_b32_e32 v162, 16, v144
	v_lshlrev_b32_e32 v162, 2, v162
	v_xor_b32_e32 v163, 32, v144
	v_lshlrev_b32_e32 v163, 2, v163
	global_load_dwordx2 v[174:175], v143, s[14:15]
	global_load_dwordx2 v[176:177], v143, s[14:15] offset:32
	global_load_dwordx2 v[178:179], v143, s[14:15] offset:256
	global_load_dwordx2 v[180:181], v143, s[14:15] offset:288
	v_add_u32_e32 v141, 0x10000, v143
	global_load_dwordx2 v[182:183], v141, s[14:15]
	global_load_dwordx2 v[184:185], v141, s[14:15] offset:32
	global_load_dwordx2 v[186:187], v141, s[14:15] offset:256
	global_load_dwordx2 v[188:189], v141, s[14:15] offset:288
	v_add_u32_e32 v141, 0x20000, v143
	global_load_dwordx2 v[190:191], v141, s[14:15]
	global_load_dwordx2 v[192:193], v141, s[14:15] offset:32
	global_load_dwordx2 v[194:195], v141, s[14:15] offset:256
	global_load_dwordx2 v[196:197], v141, s[14:15] offset:288
	v_add_u32_e32 v141, 0x30000, v143
	global_load_dwordx2 v[198:199], v141, s[14:15]
	global_load_dwordx2 v[200:201], v141, s[14:15] offset:32
	global_load_dwordx2 v[202:203], v141, s[14:15] offset:256
	global_load_dwordx2 v[204:205], v141, s[14:15] offset:288
	v_add_u32_e32 v141, 0x80000, v143
	global_load_dwordx2 v[206:207], v141, s[14:15]
	global_load_dwordx2 v[208:209], v141, s[14:15] offset:32
	global_load_dwordx2 v[210:211], v141, s[14:15] offset:256
	global_load_dwordx2 v[212:213], v141, s[14:15] offset:288
	v_add_u32_e32 v141, 0x90000, v143
	global_load_dwordx2 v[214:215], v141, s[14:15]
	global_load_dwordx2 v[216:217], v141, s[14:15] offset:32
	global_load_dwordx2 v[218:219], v141, s[14:15] offset:256
	global_load_dwordx2 v[220:221], v141, s[14:15] offset:288
	v_add_u32_e32 v141, 0xa0000, v143
	global_load_dwordx2 v[222:223], v141, s[14:15]
	global_load_dwordx2 v[224:225], v141, s[14:15] offset:32
	global_load_dwordx2 v[226:227], v141, s[14:15] offset:256
	global_load_dwordx2 v[228:229], v141, s[14:15] offset:288
	v_add_u32_e32 v141, 0xb0000, v143
	global_load_dwordx2 v[230:231], v141, s[14:15]
	global_load_dwordx2 v[232:233], v141, s[14:15] offset:32
	global_load_dwordx2 v[234:235], v141, s[14:15] offset:256
	global_load_dwordx2 v[170:171], v141, s[14:15] offset:288
	s_waitcnt vmcnt(28)
	v_lshlrev_b32_e32 v152, 16, v174
	v_and_b32_e32 v153, 0xffff0000, v174
	v_lshlrev_b32_e32 v154, 16, v175
	v_and_b32_e32 v155, 0xffff0000, v175
	v_pk_add_f32 v[126:127], v[126:127], v[154:155]
	v_pk_add_f32 v[124:125], v[124:125], v[152:153]
	v_cvt_pk_bf16_f32 v156, v124, v125
	v_cvt_pk_bf16_f32 v157, v126, v127
	v_mul_f32_e32 v164, v125, v125
	v_mul_f32_e32 v165, v127, v127
	v_fmac_f32_e32 v164, v124, v124
	v_fmac_f32_e32 v165, v126, v126
	global_store_dwordx2 v143, v[156:157], s[14:15]
	v_add_f32_e32 v158, v164, v165
	v_lshlrev_b32_e32 v152, 16, v176
	v_and_b32_e32 v153, 0xffff0000, v176
	v_lshlrev_b32_e32 v154, 16, v177
	v_and_b32_e32 v155, 0xffff0000, v177
	v_pk_add_f32 v[122:123], v[122:123], v[154:155]
	v_pk_add_f32 v[120:121], v[120:121], v[152:153]
	v_cvt_pk_bf16_f32 v156, v120, v121
	v_cvt_pk_bf16_f32 v157, v122, v123
	v_mul_f32_e32 v164, v121, v121
	v_mul_f32_e32 v165, v123, v123
	v_fmac_f32_e32 v164, v120, v120
	v_fmac_f32_e32 v165, v122, v122
	global_store_dwordx2 v143, v[156:157], s[14:15] offset:32
	v_add_f32_e32 v159, v164, v165
	v_lshlrev_b32_e32 v152, 16, v178
	v_and_b32_e32 v153, 0xffff0000, v178
	v_lshlrev_b32_e32 v154, 16, v179
	v_and_b32_e32 v155, 0xffff0000, v179
	v_pk_add_f32 v[118:119], v[118:119], v[154:155]
	v_pk_add_f32 v[116:117], v[116:117], v[152:153]
	v_cvt_pk_bf16_f32 v156, v116, v117
	v_cvt_pk_bf16_f32 v157, v118, v119
	v_mul_f32_e32 v164, v117, v117
	v_mul_f32_e32 v165, v119, v119
	v_fmac_f32_e32 v164, v116, v116
	v_fmac_f32_e32 v165, v118, v118
	global_store_dwordx2 v143, v[156:157], s[14:15] offset:256
	v_add_f32_e32 v160, v164, v165
	v_lshlrev_b32_e32 v152, 16, v180
	v_and_b32_e32 v153, 0xffff0000, v180
	v_lshlrev_b32_e32 v154, 16, v181
	v_and_b32_e32 v155, 0xffff0000, v181
	v_pk_add_f32 v[114:115], v[114:115], v[154:155]
	v_pk_add_f32 v[112:113], v[112:113], v[152:153]
	v_cvt_pk_bf16_f32 v156, v112, v113
	v_cvt_pk_bf16_f32 v157, v114, v115
	v_mul_f32_e32 v164, v113, v113
	v_mul_f32_e32 v165, v115, v115
	v_fmac_f32_e32 v164, v112, v112
	v_fmac_f32_e32 v165, v114, v114
	global_store_dwordx2 v143, v[156:157], s[14:15] offset:288
	v_add_f32_e32 v161, v164, v165
	v_add_f32_e32 v158, v158, v159
	v_add_f32_e32 v158, v158, v160
	v_add_f32_e32 v158, v158, v161
	ds_bpermute_b32 v166, v162, v158
	v_lshlrev_b32_e32 v167, 2, v142
	s_waitcnt lgkmcnt(0)
	v_add_f32_e32 v158, v158, v166
	ds_bpermute_b32 v166, v163, v158
	s_mov_b64 s[30:31], exec
	s_waitcnt lgkmcnt(0)
	v_add_f32_e32 v158, v158, v166
	s_and_b64 exec, exec, s[4:5]
	global_atomic_add_f32 v167, v158, s[16:17]
	s_mov_b64 exec, s[30:31]
	v_add_u32_e32 v141, 0x10000, v143
	s_waitcnt vmcnt(28)
	v_lshlrev_b32_e32 v152, 16, v182
	v_and_b32_e32 v153, 0xffff0000, v182
	v_lshlrev_b32_e32 v154, 16, v183
	v_and_b32_e32 v155, 0xffff0000, v183
	v_pk_add_f32 v[110:111], v[110:111], v[154:155]
	v_pk_add_f32 v[108:109], v[108:109], v[152:153]
	v_cvt_pk_bf16_f32 v156, v108, v109
	v_cvt_pk_bf16_f32 v157, v110, v111
	v_mul_f32_e32 v164, v109, v109
	v_mul_f32_e32 v165, v111, v111
	v_fmac_f32_e32 v164, v108, v108
	v_fmac_f32_e32 v165, v110, v110
	global_store_dwordx2 v141, v[156:157], s[14:15]
	v_add_f32_e32 v158, v164, v165
	v_lshlrev_b32_e32 v152, 16, v184
	v_and_b32_e32 v153, 0xffff0000, v184
	v_lshlrev_b32_e32 v154, 16, v185
	v_and_b32_e32 v155, 0xffff0000, v185
	v_pk_add_f32 v[106:107], v[106:107], v[154:155]
	v_pk_add_f32 v[104:105], v[104:105], v[152:153]
	v_cvt_pk_bf16_f32 v156, v104, v105
	v_cvt_pk_bf16_f32 v157, v106, v107
	v_mul_f32_e32 v164, v105, v105
	v_mul_f32_e32 v165, v107, v107
	v_fmac_f32_e32 v164, v104, v104
	v_fmac_f32_e32 v165, v106, v106
	global_store_dwordx2 v141, v[156:157], s[14:15] offset:32
	v_add_f32_e32 v159, v164, v165
	v_lshlrev_b32_e32 v152, 16, v186
	v_and_b32_e32 v153, 0xffff0000, v186
	v_lshlrev_b32_e32 v154, 16, v187
	v_and_b32_e32 v155, 0xffff0000, v187
	v_pk_add_f32 v[102:103], v[102:103], v[154:155]
	v_pk_add_f32 v[100:101], v[100:101], v[152:153]
	v_cvt_pk_bf16_f32 v156, v100, v101
	v_cvt_pk_bf16_f32 v157, v102, v103
	v_mul_f32_e32 v164, v101, v101
	v_mul_f32_e32 v165, v103, v103
	v_fmac_f32_e32 v164, v100, v100
	v_fmac_f32_e32 v165, v102, v102
	global_store_dwordx2 v141, v[156:157], s[14:15] offset:256
	v_add_f32_e32 v160, v164, v165
	v_lshlrev_b32_e32 v152, 16, v188
	v_and_b32_e32 v153, 0xffff0000, v188
	v_lshlrev_b32_e32 v154, 16, v189
	v_and_b32_e32 v155, 0xffff0000, v189
	v_pk_add_f32 v[98:99], v[98:99], v[154:155]
	v_pk_add_f32 v[96:97], v[96:97], v[152:153]
	v_cvt_pk_bf16_f32 v156, v96, v97
	v_cvt_pk_bf16_f32 v157, v98, v99
	v_mul_f32_e32 v164, v97, v97
	v_mul_f32_e32 v165, v99, v99
	v_fmac_f32_e32 v164, v96, v96
	v_fmac_f32_e32 v165, v98, v98
	global_store_dwordx2 v141, v[156:157], s[14:15] offset:288
	v_add_f32_e32 v161, v164, v165
	v_add_f32_e32 v158, v158, v159
	v_add_f32_e32 v158, v158, v160
	v_add_f32_e32 v158, v158, v161
	ds_bpermute_b32 v166, v162, v158
	v_add_u32_e32 v167, 0x10, v142
	v_lshlrev_b32_e32 v167, 2, v167
	s_waitcnt lgkmcnt(0)
	v_add_f32_e32 v158, v158, v166
	ds_bpermute_b32 v166, v163, v158
	s_mov_b64 s[30:31], exec
	s_waitcnt lgkmcnt(0)
	v_add_f32_e32 v158, v158, v166
	s_and_b64 exec, exec, s[4:5]
	global_atomic_add_f32 v167, v158, s[16:17]
	s_mov_b64 exec, s[30:31]
	v_add_u32_e32 v141, 0x20000, v143
	s_waitcnt vmcnt(28)
	v_lshlrev_b32_e32 v152, 16, v190
	v_and_b32_e32 v153, 0xffff0000, v190
	v_lshlrev_b32_e32 v154, 16, v191
	v_and_b32_e32 v155, 0xffff0000, v191
	v_pk_add_f32 v[94:95], v[94:95], v[154:155]
	v_pk_add_f32 v[92:93], v[92:93], v[152:153]
	v_cvt_pk_bf16_f32 v156, v92, v93
	v_cvt_pk_bf16_f32 v157, v94, v95
	v_mul_f32_e32 v164, v93, v93
	v_mul_f32_e32 v165, v95, v95
	v_fmac_f32_e32 v164, v92, v92
	v_fmac_f32_e32 v165, v94, v94
	global_store_dwordx2 v141, v[156:157], s[14:15]
	v_add_f32_e32 v158, v164, v165
	v_lshlrev_b32_e32 v152, 16, v192
	v_and_b32_e32 v153, 0xffff0000, v192
	v_lshlrev_b32_e32 v154, 16, v193
	v_and_b32_e32 v155, 0xffff0000, v193
	v_pk_add_f32 v[90:91], v[90:91], v[154:155]
	v_pk_add_f32 v[88:89], v[88:89], v[152:153]
	v_cvt_pk_bf16_f32 v156, v88, v89
	v_cvt_pk_bf16_f32 v157, v90, v91
	v_mul_f32_e32 v164, v89, v89
	v_mul_f32_e32 v165, v91, v91
	v_fmac_f32_e32 v164, v88, v88
	v_fmac_f32_e32 v165, v90, v90
	global_store_dwordx2 v141, v[156:157], s[14:15] offset:32
	v_add_f32_e32 v159, v164, v165
	v_lshlrev_b32_e32 v152, 16, v194
	v_and_b32_e32 v153, 0xffff0000, v194
	v_lshlrev_b32_e32 v154, 16, v195
	v_and_b32_e32 v155, 0xffff0000, v195
	v_pk_add_f32 v[86:87], v[86:87], v[154:155]
	v_pk_add_f32 v[84:85], v[84:85], v[152:153]
	v_cvt_pk_bf16_f32 v156, v84, v85
	v_cvt_pk_bf16_f32 v157, v86, v87
	v_mul_f32_e32 v164, v85, v85
	v_mul_f32_e32 v165, v87, v87
	v_fmac_f32_e32 v164, v84, v84
	v_fmac_f32_e32 v165, v86, v86
	global_store_dwordx2 v141, v[156:157], s[14:15] offset:256
	v_add_f32_e32 v160, v164, v165
	v_lshlrev_b32_e32 v152, 16, v196
	v_and_b32_e32 v153, 0xffff0000, v196
	v_lshlrev_b32_e32 v154, 16, v197
	v_and_b32_e32 v155, 0xffff0000, v197
	v_pk_add_f32 v[82:83], v[82:83], v[154:155]
	v_pk_add_f32 v[80:81], v[80:81], v[152:153]
	v_cvt_pk_bf16_f32 v156, v80, v81
	v_cvt_pk_bf16_f32 v157, v82, v83
	v_mul_f32_e32 v164, v81, v81
	v_mul_f32_e32 v165, v83, v83
	v_fmac_f32_e32 v164, v80, v80
	v_fmac_f32_e32 v165, v82, v82
	global_store_dwordx2 v141, v[156:157], s[14:15] offset:288
	v_add_f32_e32 v161, v164, v165
	v_add_f32_e32 v158, v158, v159
	v_add_f32_e32 v158, v158, v160
	v_add_f32_e32 v158, v158, v161
	ds_bpermute_b32 v166, v162, v158
	v_add_u32_e32 v167, 0x20, v142
	v_lshlrev_b32_e32 v167, 2, v167
	s_waitcnt lgkmcnt(0)
	v_add_f32_e32 v158, v158, v166
	ds_bpermute_b32 v166, v163, v158
	s_mov_b64 s[30:31], exec
	s_waitcnt lgkmcnt(0)
	v_add_f32_e32 v158, v158, v166
	s_and_b64 exec, exec, s[4:5]
	global_atomic_add_f32 v167, v158, s[16:17]
	s_mov_b64 exec, s[30:31]
	v_add_u32_e32 v141, 0x30000, v143
	s_waitcnt vmcnt(28)
	v_lshlrev_b32_e32 v152, 16, v198
	v_and_b32_e32 v153, 0xffff0000, v198
	v_lshlrev_b32_e32 v154, 16, v199
	v_and_b32_e32 v155, 0xffff0000, v199
	v_pk_add_f32 v[78:79], v[78:79], v[154:155]
	v_pk_add_f32 v[76:77], v[76:77], v[152:153]
	v_cvt_pk_bf16_f32 v156, v76, v77
	v_cvt_pk_bf16_f32 v157, v78, v79
	v_mul_f32_e32 v164, v77, v77
	v_mul_f32_e32 v165, v79, v79
	v_fmac_f32_e32 v164, v76, v76
	v_fmac_f32_e32 v165, v78, v78
	global_store_dwordx2 v141, v[156:157], s[14:15]
	v_add_f32_e32 v158, v164, v165
	v_lshlrev_b32_e32 v152, 16, v200
	v_and_b32_e32 v153, 0xffff0000, v200
	v_lshlrev_b32_e32 v154, 16, v201
	v_and_b32_e32 v155, 0xffff0000, v201
	v_pk_add_f32 v[74:75], v[74:75], v[154:155]
	v_pk_add_f32 v[72:73], v[72:73], v[152:153]
	v_cvt_pk_bf16_f32 v156, v72, v73
	v_cvt_pk_bf16_f32 v157, v74, v75
	v_mul_f32_e32 v164, v73, v73
	v_mul_f32_e32 v165, v75, v75
	v_fmac_f32_e32 v164, v72, v72
	v_fmac_f32_e32 v165, v74, v74
	global_store_dwordx2 v141, v[156:157], s[14:15] offset:32
	v_add_f32_e32 v159, v164, v165
	v_lshlrev_b32_e32 v152, 16, v202
	v_and_b32_e32 v153, 0xffff0000, v202
	v_lshlrev_b32_e32 v154, 16, v203
	v_and_b32_e32 v155, 0xffff0000, v203
	v_pk_add_f32 v[70:71], v[70:71], v[154:155]
	v_pk_add_f32 v[68:69], v[68:69], v[152:153]
	v_cvt_pk_bf16_f32 v156, v68, v69
	v_cvt_pk_bf16_f32 v157, v70, v71
	v_mul_f32_e32 v164, v69, v69
	v_mul_f32_e32 v165, v71, v71
	v_fmac_f32_e32 v164, v68, v68
	v_fmac_f32_e32 v165, v70, v70
	global_store_dwordx2 v141, v[156:157], s[14:15] offset:256
	v_add_f32_e32 v160, v164, v165
	v_lshlrev_b32_e32 v152, 16, v204
	v_and_b32_e32 v153, 0xffff0000, v204
	v_lshlrev_b32_e32 v154, 16, v205
	v_and_b32_e32 v155, 0xffff0000, v205
	v_pk_add_f32 v[66:67], v[66:67], v[154:155]
	v_pk_add_f32 v[64:65], v[64:65], v[152:153]
	v_cvt_pk_bf16_f32 v156, v64, v65
	v_cvt_pk_bf16_f32 v157, v66, v67
	v_mul_f32_e32 v164, v65, v65
	v_mul_f32_e32 v165, v67, v67
	v_fmac_f32_e32 v164, v64, v64
	v_fmac_f32_e32 v165, v66, v66
	global_store_dwordx2 v141, v[156:157], s[14:15] offset:288
	v_add_f32_e32 v161, v164, v165
	v_add_f32_e32 v158, v158, v159
	v_add_f32_e32 v158, v158, v160
	v_add_f32_e32 v158, v158, v161
	ds_bpermute_b32 v166, v162, v158
	v_add_u32_e32 v167, 0x30, v142
	v_lshlrev_b32_e32 v167, 2, v167
	s_waitcnt lgkmcnt(0)
	v_add_f32_e32 v158, v158, v166
	ds_bpermute_b32 v166, v163, v158
	s_mov_b64 s[30:31], exec
	s_waitcnt lgkmcnt(0)
	v_add_f32_e32 v158, v158, v166
	s_and_b64 exec, exec, s[4:5]
	global_atomic_add_f32 v167, v158, s[16:17]
	s_mov_b64 exec, s[30:31]
	v_add_u32_e32 v141, 0x80000, v143
	s_waitcnt vmcnt(28)
	v_lshlrev_b32_e32 v152, 16, v206
	v_and_b32_e32 v153, 0xffff0000, v206
	v_lshlrev_b32_e32 v154, 16, v207
	v_and_b32_e32 v155, 0xffff0000, v207
	v_pk_add_f32 v[62:63], v[62:63], v[154:155]
	v_pk_add_f32 v[60:61], v[60:61], v[152:153]
	v_cvt_pk_bf16_f32 v156, v60, v61
	v_cvt_pk_bf16_f32 v157, v62, v63
	v_mul_f32_e32 v164, v61, v61
	v_mul_f32_e32 v165, v63, v63
	v_fmac_f32_e32 v164, v60, v60
	v_fmac_f32_e32 v165, v62, v62
	global_store_dwordx2 v141, v[156:157], s[14:15]
	v_add_f32_e32 v158, v164, v165
	v_lshlrev_b32_e32 v152, 16, v208
	v_and_b32_e32 v153, 0xffff0000, v208
	v_lshlrev_b32_e32 v154, 16, v209
	v_and_b32_e32 v155, 0xffff0000, v209
	v_pk_add_f32 v[58:59], v[58:59], v[154:155]
	v_pk_add_f32 v[56:57], v[56:57], v[152:153]
	v_cvt_pk_bf16_f32 v156, v56, v57
	v_cvt_pk_bf16_f32 v157, v58, v59
	v_mul_f32_e32 v164, v57, v57
	v_mul_f32_e32 v165, v59, v59
	v_fmac_f32_e32 v164, v56, v56
	v_fmac_f32_e32 v165, v58, v58
	global_store_dwordx2 v141, v[156:157], s[14:15] offset:32
	v_add_f32_e32 v159, v164, v165
	v_lshlrev_b32_e32 v152, 16, v210
	v_and_b32_e32 v153, 0xffff0000, v210
	v_lshlrev_b32_e32 v154, 16, v211
	v_and_b32_e32 v155, 0xffff0000, v211
	v_pk_add_f32 v[54:55], v[54:55], v[154:155]
	v_pk_add_f32 v[52:53], v[52:53], v[152:153]
	v_cvt_pk_bf16_f32 v156, v52, v53
	v_cvt_pk_bf16_f32 v157, v54, v55
	v_mul_f32_e32 v164, v53, v53
	v_mul_f32_e32 v165, v55, v55
	v_fmac_f32_e32 v164, v52, v52
	v_fmac_f32_e32 v165, v54, v54
	global_store_dwordx2 v141, v[156:157], s[14:15] offset:256
	v_add_f32_e32 v160, v164, v165
	v_lshlrev_b32_e32 v152, 16, v212
	v_and_b32_e32 v153, 0xffff0000, v212
	v_lshlrev_b32_e32 v154, 16, v213
	v_and_b32_e32 v155, 0xffff0000, v213
	v_pk_add_f32 v[50:51], v[50:51], v[154:155]
	v_pk_add_f32 v[48:49], v[48:49], v[152:153]
	v_cvt_pk_bf16_f32 v156, v48, v49
	v_cvt_pk_bf16_f32 v157, v50, v51
	v_mul_f32_e32 v164, v49, v49
	v_mul_f32_e32 v165, v51, v51
	v_fmac_f32_e32 v164, v48, v48
	v_fmac_f32_e32 v165, v50, v50
	global_store_dwordx2 v141, v[156:157], s[14:15] offset:288
	v_add_f32_e32 v161, v164, v165
	v_add_f32_e32 v158, v158, v159
	v_add_f32_e32 v158, v158, v160
	v_add_f32_e32 v158, v158, v161
	ds_bpermute_b32 v166, v162, v158
	v_add_u32_e32 v167, 0x80, v142
	v_lshlrev_b32_e32 v167, 2, v167
	s_waitcnt lgkmcnt(0)
	v_add_f32_e32 v158, v158, v166
	ds_bpermute_b32 v166, v163, v158
	s_mov_b64 s[30:31], exec
	s_waitcnt lgkmcnt(0)
	v_add_f32_e32 v158, v158, v166
	s_and_b64 exec, exec, s[4:5]
	global_atomic_add_f32 v167, v158, s[16:17]
	s_mov_b64 exec, s[30:31]
	v_add_u32_e32 v141, 0x90000, v143
	s_waitcnt vmcnt(28)
	v_lshlrev_b32_e32 v152, 16, v214
	v_and_b32_e32 v153, 0xffff0000, v214
	v_lshlrev_b32_e32 v154, 16, v215
	v_and_b32_e32 v155, 0xffff0000, v215
	v_pk_add_f32 v[46:47], v[46:47], v[154:155]
	v_pk_add_f32 v[44:45], v[44:45], v[152:153]
	v_cvt_pk_bf16_f32 v156, v44, v45
	v_cvt_pk_bf16_f32 v157, v46, v47
	v_mul_f32_e32 v164, v45, v45
	v_mul_f32_e32 v165, v47, v47
	v_fmac_f32_e32 v164, v44, v44
	v_fmac_f32_e32 v165, v46, v46
	global_store_dwordx2 v141, v[156:157], s[14:15]
	v_add_f32_e32 v158, v164, v165
	v_lshlrev_b32_e32 v152, 16, v216
	v_and_b32_e32 v153, 0xffff0000, v216
	v_lshlrev_b32_e32 v154, 16, v217
	v_and_b32_e32 v155, 0xffff0000, v217
	v_pk_add_f32 v[42:43], v[42:43], v[154:155]
	v_pk_add_f32 v[40:41], v[40:41], v[152:153]
	v_cvt_pk_bf16_f32 v156, v40, v41
	v_cvt_pk_bf16_f32 v157, v42, v43
	v_mul_f32_e32 v164, v41, v41
	v_mul_f32_e32 v165, v43, v43
	v_fmac_f32_e32 v164, v40, v40
	v_fmac_f32_e32 v165, v42, v42
	global_store_dwordx2 v141, v[156:157], s[14:15] offset:32
	v_add_f32_e32 v159, v164, v165
	v_lshlrev_b32_e32 v152, 16, v218
	v_and_b32_e32 v153, 0xffff0000, v218
	v_lshlrev_b32_e32 v154, 16, v219
	v_and_b32_e32 v155, 0xffff0000, v219
	v_pk_add_f32 v[38:39], v[38:39], v[154:155]
	v_pk_add_f32 v[36:37], v[36:37], v[152:153]
	v_cvt_pk_bf16_f32 v156, v36, v37
	v_cvt_pk_bf16_f32 v157, v38, v39
	v_mul_f32_e32 v164, v37, v37
	v_mul_f32_e32 v165, v39, v39
	v_fmac_f32_e32 v164, v36, v36
	v_fmac_f32_e32 v165, v38, v38
	global_store_dwordx2 v141, v[156:157], s[14:15] offset:256
	v_add_f32_e32 v160, v164, v165
	v_lshlrev_b32_e32 v152, 16, v220
	v_and_b32_e32 v153, 0xffff0000, v220
	v_lshlrev_b32_e32 v154, 16, v221
	v_and_b32_e32 v155, 0xffff0000, v221
	v_pk_add_f32 v[34:35], v[34:35], v[154:155]
	v_pk_add_f32 v[32:33], v[32:33], v[152:153]
	v_cvt_pk_bf16_f32 v156, v32, v33
	v_cvt_pk_bf16_f32 v157, v34, v35
	v_mul_f32_e32 v164, v33, v33
	v_mul_f32_e32 v165, v35, v35
	v_fmac_f32_e32 v164, v32, v32
	v_fmac_f32_e32 v165, v34, v34
	global_store_dwordx2 v141, v[156:157], s[14:15] offset:288
	v_add_f32_e32 v161, v164, v165
	v_add_f32_e32 v158, v158, v159
	v_add_f32_e32 v158, v158, v160
	v_add_f32_e32 v158, v158, v161
	ds_bpermute_b32 v166, v162, v158
	v_add_u32_e32 v167, 0x90, v142
	v_lshlrev_b32_e32 v167, 2, v167
	s_waitcnt lgkmcnt(0)
	v_add_f32_e32 v158, v158, v166
	ds_bpermute_b32 v166, v163, v158
	s_mov_b64 s[30:31], exec
	s_waitcnt lgkmcnt(0)
	v_add_f32_e32 v158, v158, v166
	s_and_b64 exec, exec, s[4:5]
	global_atomic_add_f32 v167, v158, s[16:17]
	s_mov_b64 exec, s[30:31]
	v_add_u32_e32 v141, 0xa0000, v143
	s_waitcnt vmcnt(28)
	v_lshlrev_b32_e32 v152, 16, v222
	v_and_b32_e32 v153, 0xffff0000, v222
	v_lshlrev_b32_e32 v154, 16, v223
	v_and_b32_e32 v155, 0xffff0000, v223
	v_pk_add_f32 v[30:31], v[30:31], v[154:155]
	v_pk_add_f32 v[28:29], v[28:29], v[152:153]
	v_cvt_pk_bf16_f32 v156, v28, v29
	v_cvt_pk_bf16_f32 v157, v30, v31
	v_mul_f32_e32 v164, v29, v29
	v_mul_f32_e32 v165, v31, v31
	v_fmac_f32_e32 v164, v28, v28
	v_fmac_f32_e32 v165, v30, v30
	global_store_dwordx2 v141, v[156:157], s[14:15]
	v_add_f32_e32 v158, v164, v165
	v_lshlrev_b32_e32 v152, 16, v224
	v_and_b32_e32 v153, 0xffff0000, v224
	v_lshlrev_b32_e32 v154, 16, v225
	v_and_b32_e32 v155, 0xffff0000, v225
	v_pk_add_f32 v[26:27], v[26:27], v[154:155]
	v_pk_add_f32 v[24:25], v[24:25], v[152:153]
	v_cvt_pk_bf16_f32 v156, v24, v25
	v_cvt_pk_bf16_f32 v157, v26, v27
	v_mul_f32_e32 v164, v25, v25
	v_mul_f32_e32 v165, v27, v27
	v_fmac_f32_e32 v164, v24, v24
	v_fmac_f32_e32 v165, v26, v26
	global_store_dwordx2 v141, v[156:157], s[14:15] offset:32
	v_add_f32_e32 v159, v164, v165
	v_lshlrev_b32_e32 v152, 16, v226
	v_and_b32_e32 v153, 0xffff0000, v226
	v_lshlrev_b32_e32 v154, 16, v227
	v_and_b32_e32 v155, 0xffff0000, v227
	v_pk_add_f32 v[22:23], v[22:23], v[154:155]
	v_pk_add_f32 v[20:21], v[20:21], v[152:153]
	v_cvt_pk_bf16_f32 v156, v20, v21
	v_cvt_pk_bf16_f32 v157, v22, v23
	v_mul_f32_e32 v164, v21, v21
	v_mul_f32_e32 v165, v23, v23
	v_fmac_f32_e32 v164, v20, v20
	v_fmac_f32_e32 v165, v22, v22
	global_store_dwordx2 v141, v[156:157], s[14:15] offset:256
	v_add_f32_e32 v160, v164, v165
	v_lshlrev_b32_e32 v152, 16, v228
	v_and_b32_e32 v153, 0xffff0000, v228
	v_lshlrev_b32_e32 v154, 16, v229
	v_and_b32_e32 v155, 0xffff0000, v229
	v_pk_add_f32 v[18:19], v[18:19], v[154:155]
	v_pk_add_f32 v[16:17], v[16:17], v[152:153]
	v_cvt_pk_bf16_f32 v156, v16, v17
	v_cvt_pk_bf16_f32 v157, v18, v19
	v_mul_f32_e32 v164, v17, v17
	v_mul_f32_e32 v165, v19, v19
	v_fmac_f32_e32 v164, v16, v16
	v_fmac_f32_e32 v165, v18, v18
	global_store_dwordx2 v141, v[156:157], s[14:15] offset:288
	v_add_f32_e32 v161, v164, v165
	v_add_f32_e32 v158, v158, v159
	v_add_f32_e32 v158, v158, v160
	v_add_f32_e32 v158, v158, v161
	ds_bpermute_b32 v166, v162, v158
	v_add_u32_e32 v167, 0xa0, v142
	v_lshlrev_b32_e32 v167, 2, v167
	s_waitcnt lgkmcnt(0)
	v_add_f32_e32 v158, v158, v166
	ds_bpermute_b32 v166, v163, v158
	s_mov_b64 s[30:31], exec
	s_waitcnt lgkmcnt(0)
	v_add_f32_e32 v158, v158, v166
	s_and_b64 exec, exec, s[4:5]
	global_atomic_add_f32 v167, v158, s[16:17]
	s_mov_b64 exec, s[30:31]
	v_add_u32_e32 v141, 0xb0000, v143
	s_waitcnt vmcnt(28)
	v_lshlrev_b32_e32 v152, 16, v230
	v_and_b32_e32 v153, 0xffff0000, v230
	v_lshlrev_b32_e32 v154, 16, v231
	v_and_b32_e32 v155, 0xffff0000, v231
	v_pk_add_f32 v[14:15], v[14:15], v[154:155]
	v_pk_add_f32 v[12:13], v[12:13], v[152:153]
	v_cvt_pk_bf16_f32 v156, v12, v13
	v_cvt_pk_bf16_f32 v157, v14, v15
	v_mul_f32_e32 v164, v13, v13
	v_mul_f32_e32 v165, v15, v15
	v_fmac_f32_e32 v164, v12, v12
	v_fmac_f32_e32 v165, v14, v14
	global_store_dwordx2 v141, v[156:157], s[14:15]
	v_add_f32_e32 v158, v164, v165
	v_lshlrev_b32_e32 v152, 16, v232
	v_and_b32_e32 v153, 0xffff0000, v232
	v_lshlrev_b32_e32 v154, 16, v233
	v_and_b32_e32 v155, 0xffff0000, v233
	v_pk_add_f32 v[10:11], v[10:11], v[154:155]
	v_pk_add_f32 v[8:9], v[8:9], v[152:153]
	v_cvt_pk_bf16_f32 v156, v8, v9
	v_cvt_pk_bf16_f32 v157, v10, v11
	v_mul_f32_e32 v164, v9, v9
	v_mul_f32_e32 v165, v11, v11
	v_fmac_f32_e32 v164, v8, v8
	v_fmac_f32_e32 v165, v10, v10
	global_store_dwordx2 v141, v[156:157], s[14:15] offset:32
	v_add_f32_e32 v159, v164, v165
	v_lshlrev_b32_e32 v152, 16, v234
	v_and_b32_e32 v153, 0xffff0000, v234
	v_lshlrev_b32_e32 v154, 16, v235
	v_and_b32_e32 v155, 0xffff0000, v235
	v_pk_add_f32 v[6:7], v[6:7], v[154:155]
	v_pk_add_f32 v[4:5], v[4:5], v[152:153]
	v_cvt_pk_bf16_f32 v156, v4, v5
	v_cvt_pk_bf16_f32 v157, v6, v7
	v_mul_f32_e32 v164, v5, v5
	v_mul_f32_e32 v165, v7, v7
	v_fmac_f32_e32 v164, v4, v4
	v_fmac_f32_e32 v165, v6, v6
	global_store_dwordx2 v141, v[156:157], s[14:15] offset:256
	v_add_f32_e32 v160, v164, v165
	v_lshlrev_b32_e32 v152, 16, v170
	v_and_b32_e32 v153, 0xffff0000, v170
	v_lshlrev_b32_e32 v154, 16, v171
	v_and_b32_e32 v155, 0xffff0000, v171
	v_pk_add_f32 v[2:3], v[2:3], v[154:155]
	v_pk_add_f32 v[0:1], v[0:1], v[152:153]
	v_cvt_pk_bf16_f32 v156, v0, v1
	v_cvt_pk_bf16_f32 v157, v2, v3
	v_mul_f32_e32 v164, v1, v1
	v_mul_f32_e32 v165, v3, v3
	v_fmac_f32_e32 v164, v0, v0
	v_fmac_f32_e32 v165, v2, v2
	global_store_dwordx2 v141, v[156:157], s[14:15] offset:288
	v_add_f32_e32 v161, v164, v165
	v_add_f32_e32 v158, v158, v159
	v_add_f32_e32 v158, v158, v160
	v_add_f32_e32 v158, v158, v161
	ds_bpermute_b32 v166, v162, v158
	v_add_u32_e32 v167, 0xb0, v142
	v_lshlrev_b32_e32 v167, 2, v167
	s_waitcnt lgkmcnt(0)
	v_add_f32_e32 v158, v158, v166
	ds_bpermute_b32 v166, v163, v158
	s_mov_b64 s[30:31], exec
	s_waitcnt lgkmcnt(0)
	v_add_f32_e32 v158, v158, v166
	s_and_b64 exec, exec, s[4:5]
	global_atomic_add_f32 v167, v158, s[16:17]
	s_mov_b64 exec, s[30:31]
